# dense attention MFMA segment: fourth fragment buffer v[240:243] (constants restored after loop): reads never target a buffer read by a recent MFMA (v61 + n4)
# speedup vs baseline: 1.0382x; 1.0382x over previous
.LBB0_1013:
	s_waitcnt lgkmcnt(1)
	v_mfma_f32_32x32x16_bf16 v[50:65], v[226:229], v[170:173], v[50:65]
	ds_read_b128 v[246:249], v235 offset:32
	v_mfma_f32_32x32x16_bf16 v[16:31], v[226:229], v[174:177], v[16:31]
	s_add_i32 s44, s4, 1
	s_and_b32 s43, s44, 1
	s_mul_i32 s43, s43, 0x2400
	s_waitcnt lgkmcnt(1)
	v_mfma_f32_32x32x16_bf16 v[34:49], v[230:233], v[170:173], v[34:49]
	ds_read_b128 v[240:243], v235 offset:4640
	v_add_u32_e32 v198, s43, v203
	v_add_u32_e32 v199, s42, v203
	v_mfma_f32_32x32x16_bf16 v[0:15], v[230:233], v[174:177], v[0:15]
	s_add_i32 s16, s4, 2
	s_min_u32 s16, s16, 63
	s_waitcnt lgkmcnt(1)
	v_mfma_f32_32x32x16_bf16 v[50:65], v[246:249], v[166:169], v[50:65]
	ds_read_b128 v[226:229], v235 offset:64
	v_mfma_f32_32x32x16_bf16 v[16:31], v[246:249], v[162:165], v[16:31]
	s_waitcnt lgkmcnt(1)
	v_mfma_f32_32x32x16_bf16 v[34:49], v[240:243], v[166:169], v[34:49]
	ds_read_b128 v[230:233], v235 offset:4672
	v_mfma_f32_32x32x16_bf16 v[0:15], v[240:243], v[162:165], v[0:15]
	s_waitcnt lgkmcnt(1)
	v_mfma_f32_32x32x16_bf16 v[50:65], v[226:229], v[186:189], v[50:65]
	ds_read_b128 v[246:249], v235 offset:96
	v_mfma_f32_32x32x16_bf16 v[16:31], v[226:229], v[218:221], v[16:31]
	s_waitcnt lgkmcnt(1)
	v_mfma_f32_32x32x16_bf16 v[34:49], v[230:233], v[186:189], v[34:49]
	ds_read_b128 v[240:243], v235 offset:4704
	v_mfma_f32_32x32x16_bf16 v[0:15], v[230:233], v[218:221], v[0:15]
	s_waitcnt lgkmcnt(1)
	v_mfma_f32_32x32x16_bf16 v[50:65], v[246:249], v[190:193], v[50:65]
	ds_read_b128 v[226:229], v234
	v_mfma_f32_32x32x16_bf16 v[16:31], v[246:249], v[222:225], v[16:31]
	s_waitcnt lgkmcnt(1)
	v_mfma_f32_32x32x16_bf16 v[34:49], v[240:243], v[190:193], v[34:49]
	ds_read_b128 v[230:233], v234 offset:32
	v_mfma_f32_32x32x16_bf16 v[0:15], v[240:243], v[222:225], v[0:15]
	s_waitcnt lgkmcnt(1)
	v_mfma_f32_32x32x16_bf16 v[114:129], v[226:229], v[130:133], 0
	ds_read_b128 v[246:249], v234 offset:64
	v_mfma_f32_32x32x16_bf16 v[98:113], v[226:229], v[146:149], 0
	s_waitcnt lgkmcnt(1)
	v_mfma_f32_32x32x16_bf16 v[114:129], v[230:233], v[134:137], v[114:129]
	ds_read_b128 v[240:243], v234 offset:96
	s_waitcnt vmcnt(0)
	ds_write_b128 v199, v[178:181]
	v_mfma_f32_32x32x16_bf16 v[98:113], v[230:233], v[150:153], v[98:113]
	s_waitcnt lgkmcnt(2)
	v_mfma_f32_32x32x16_bf16 v[114:129], v[246:249], v[138:141], v[114:129]
	ds_read_b128 v[226:229], v234 offset:4608
	ds_write_b128 v198, v[182:185]
	v_mfma_f32_32x32x16_bf16 v[98:113], v[246:249], v[154:157], v[98:113]
	s_waitcnt lgkmcnt(3)
	v_mfma_f32_32x32x16_bf16 v[114:129], v[240:243], v[142:145], v[114:129]
	ds_read_b128 v[230:233], v234 offset:4640
	s_lshl_b64 s[6:7], s[16:17], 13
	v_lshl_add_u64 v[182:183], v[212:213], 0, s[6:7]
	v_mfma_f32_32x32x16_bf16 v[98:113], v[240:243], v[158:161], v[98:113]
	global_load_dwordx4 v[182:185], v[182:183], off
	s_lshl_b64 s[6:7], s[16:17], 7
	s_waitcnt lgkmcnt(2)
	v_mfma_f32_32x32x16_bf16 v[82:97], v[226:229], v[130:133], 0
	ds_read_b128 v[246:249], v234 offset:4672
	v_lshl_add_u64 v[178:179], v[214:215], 0, s[6:7]
	v_mfma_f32_32x32x16_bf16 v[66:81], v[226:229], v[146:149], 0
	global_load_dwordx4 v[178:181], v[178:179], off
	s_waitcnt lgkmcnt(1)
	v_mfma_f32_32x32x16_bf16 v[82:97], v[230:233], v[134:137], v[82:97]
	ds_read_b128 v[240:243], v234 offset:4704
	v_mfma_f32_32x32x16_bf16 v[66:81], v[230:233], v[150:153], v[66:81]
	s_waitcnt lgkmcnt(1)
	v_mfma_f32_32x32x16_bf16 v[82:97], v[246:249], v[138:141], v[82:97]
	v_mfma_f32_32x32x16_bf16 v[66:81], v[246:249], v[154:157], v[66:81]
	s_waitcnt lgkmcnt(0)
	v_mfma_f32_32x32x16_bf16 v[82:97], v[240:243], v[142:145], v[82:97]
	v_mfma_f32_32x32x16_bf16 v[66:81], v[240:243], v[158:161], v[66:81]
	s_cmp_eq_u32 s101, 1
	s_cbranch_scc0 .Lpp_nb_l1
	s_barrier

.Lpp_nb_l2:
	s_cmp_eq_u32 s44, 63
	s_cbranch_scc0 .LBB0_1013
	s_waitcnt lgkmcnt(1)
	v_mfma_f32_32x32x16_bf16 v[50:65], v[226:229], v[170:173], v[50:65]
	ds_read_b128 v[246:249], v235 offset:32
	v_mfma_f32_32x32x16_bf16 v[16:31], v[226:229], v[174:177], v[16:31]
	s_waitcnt lgkmcnt(1)
	v_mfma_f32_32x32x16_bf16 v[34:49], v[230:233], v[170:173], v[34:49]
	ds_read_b128 v[240:243], v235 offset:4640
	v_mfma_f32_32x32x16_bf16 v[0:15], v[230:233], v[174:177], v[0:15]
	s_waitcnt lgkmcnt(1)
	v_mfma_f32_32x32x16_bf16 v[50:65], v[246:249], v[166:169], v[50:65]
	ds_read_b128 v[226:229], v235 offset:64
	v_mfma_f32_32x32x16_bf16 v[16:31], v[246:249], v[162:165], v[16:31]
	s_waitcnt lgkmcnt(1)
	v_mfma_f32_32x32x16_bf16 v[34:49], v[240:243], v[166:169], v[34:49]
	ds_read_b128 v[230:233], v235 offset:4672
	v_mfma_f32_32x32x16_bf16 v[0:15], v[240:243], v[162:165], v[0:15]
	s_waitcnt lgkmcnt(1)
	v_mfma_f32_32x32x16_bf16 v[50:65], v[226:229], v[186:189], v[50:65]
	ds_read_b128 v[246:249], v235 offset:96
	v_mfma_f32_32x32x16_bf16 v[16:31], v[226:229], v[218:221], v[16:31]
	s_waitcnt lgkmcnt(1)
	v_mfma_f32_32x32x16_bf16 v[34:49], v[230:233], v[186:189], v[34:49]
	ds_read_b128 v[240:243], v235 offset:4704
	v_mfma_f32_32x32x16_bf16 v[0:15], v[230:233], v[218:221], v[0:15]
	s_waitcnt lgkmcnt(1)
	v_mfma_f32_32x32x16_bf16 v[50:65], v[246:249], v[190:193], v[50:65]
	ds_read_b128 v[226:229], v234
	v_mfma_f32_32x32x16_bf16 v[16:31], v[246:249], v[222:225], v[16:31]
	s_waitcnt lgkmcnt(1)
	v_mfma_f32_32x32x16_bf16 v[34:49], v[240:243], v[190:193], v[34:49]
	ds_read_b128 v[230:233], v234 offset:32
	v_mfma_f32_32x32x16_bf16 v[0:15], v[240:243], v[222:225], v[0:15]
	s_waitcnt lgkmcnt(1)
	v_mfma_f32_32x32x16_bf16 v[114:129], v[226:229], v[130:133], 0
	ds_read_b128 v[246:249], v234 offset:64
	v_mfma_f32_32x32x16_bf16 v[98:113], v[226:229], v[146:149], 0
	s_waitcnt lgkmcnt(1)
	v_mfma_f32_32x32x16_bf16 v[114:129], v[230:233], v[134:137], v[114:129]
	ds_read_b128 v[240:243], v234 offset:96
	v_mfma_f32_32x32x16_bf16 v[98:113], v[230:233], v[150:153], v[98:113]
	s_waitcnt lgkmcnt(1)
	v_mfma_f32_32x32x16_bf16 v[114:129], v[246:249], v[138:141], v[114:129]
	ds_read_b128 v[226:229], v234 offset:4608
	v_mfma_f32_32x32x16_bf16 v[98:113], v[246:249], v[154:157], v[98:113]
	s_waitcnt lgkmcnt(1)
	v_mfma_f32_32x32x16_bf16 v[114:129], v[240:243], v[142:145], v[114:129]
	ds_read_b128 v[230:233], v234 offset:4640
	v_mfma_f32_32x32x16_bf16 v[98:113], v[240:243], v[158:161], v[98:113]
	s_waitcnt lgkmcnt(1)
	v_mfma_f32_32x32x16_bf16 v[82:97], v[226:229], v[130:133], 0
	ds_read_b128 v[246:249], v234 offset:4672
	v_mfma_f32_32x32x16_bf16 v[66:81], v[226:229], v[146:149], 0
	s_waitcnt lgkmcnt(1)
	v_mfma_f32_32x32x16_bf16 v[82:97], v[230:233], v[134:137], v[82:97]
	ds_read_b128 v[240:243], v234 offset:4704
	v_mfma_f32_32x32x16_bf16 v[66:81], v[230:233], v[150:153], v[66:81]
	s_waitcnt lgkmcnt(1)
	v_mfma_f32_32x32x16_bf16 v[82:97], v[246:249], v[138:141], v[82:97]
	v_mfma_f32_32x32x16_bf16 v[66:81], v[246:249], v[154:157], v[66:81]
	s_waitcnt lgkmcnt(0)
	v_mfma_f32_32x32x16_bf16 v[82:97], v[240:243], v[142:145], v[82:97]
	v_mfma_f32_32x32x16_bf16 v[66:81], v[240:243], v[158:161], v[66:81]
	s_cmp_eq_u32 s101, 1
	s_cbranch_scc0 .Lpp_nb_p1
	s_barrier
.Lpp_nb_p1:
	v_exp_f32_e32 v114, v114
	v_exp_f32_e32 v115, v115
	v_exp_f32_e32 v116, v116
	v_exp_f32_e32 v117, v117
	v_exp_f32_e32 v118, v118
	v_exp_f32_e32 v119, v119
	v_exp_f32_e32 v120, v120
	v_exp_f32_e32 v121, v121
	v_cvt_pk_bf16_f32 v170, v114, v115
	v_add_f32_e32 v114, v114, v115
	v_exp_f32_e32 v122, v122
	v_exp_f32_e32 v123, v123
	v_cvt_pk_bf16_f32 v171, v116, v117
	v_add_f32_e32 v116, v116, v117
	v_add_f32_e32 v217, v217, v114
	v_exp_f32_e32 v124, v124
	v_exp_f32_e32 v125, v125
	v_cvt_pk_bf16_f32 v172, v118, v119
	v_add_f32_e32 v118, v118, v119
	v_add_f32_e32 v217, v217, v116
	v_exp_f32_e32 v126, v126
	v_exp_f32_e32 v127, v127
	v_cvt_pk_bf16_f32 v173, v120, v121
	v_add_f32_e32 v120, v120, v121
	v_add_f32_e32 v217, v217, v118
	v_exp_f32_e32 v128, v128
	v_exp_f32_e32 v129, v129
	v_cvt_pk_bf16_f32 v166, v122, v123
	v_add_f32_e32 v122, v122, v123
	v_add_f32_e32 v217, v217, v120
	v_exp_f32_e32 v98, v98
	v_exp_f32_e32 v99, v99
	v_cvt_pk_bf16_f32 v167, v124, v125
	v_add_f32_e32 v124, v124, v125
	v_add_f32_e32 v217, v217, v122
	v_exp_f32_e32 v100, v100
	v_exp_f32_e32 v101, v101
	v_cvt_pk_bf16_f32 v168, v126, v127
	v_add_f32_e32 v126, v126, v127
	v_add_f32_e32 v217, v217, v124
	v_exp_f32_e32 v102, v102
	v_exp_f32_e32 v103, v103
	v_cvt_pk_bf16_f32 v169, v128, v129
	v_add_f32_e32 v128, v128, v129
	v_add_f32_e32 v217, v217, v126
	v_exp_f32_e32 v104, v104
	v_exp_f32_e32 v105, v105
	v_cvt_pk_bf16_f32 v174, v98, v99
	v_add_f32_e32 v98, v98, v99
	v_add_f32_e32 v217, v217, v128
	v_exp_f32_e32 v106, v106
	v_exp_f32_e32 v107, v107
	v_cvt_pk_bf16_f32 v175, v100, v101
	v_add_f32_e32 v100, v100, v101
	v_add_f32_e32 v216, v216, v98
	v_exp_f32_e32 v108, v108
	v_exp_f32_e32 v109, v109
	v_cvt_pk_bf16_f32 v176, v102, v103
	v_add_f32_e32 v102, v102, v103
	v_add_f32_e32 v216, v216, v100
	v_exp_f32_e32 v110, v110
	v_exp_f32_e32 v111, v111
	v_cvt_pk_bf16_f32 v177, v104, v105
	v_add_f32_e32 v104, v104, v105
	v_add_f32_e32 v216, v216, v102
	v_exp_f32_e32 v112, v112
	v_exp_f32_e32 v113, v113
	v_cvt_pk_bf16_f32 v162, v106, v107
	v_add_f32_e32 v106, v106, v107
	v_add_f32_e32 v216, v216, v104
	v_cvt_pk_bf16_f32 v163, v108, v109
	v_add_f32_e32 v108, v108, v109
	v_add_f32_e32 v216, v216, v106
	v_cvt_pk_bf16_f32 v164, v110, v111
	v_add_f32_e32 v110, v110, v111
	v_add_f32_e32 v216, v216, v108
	v_cvt_pk_bf16_f32 v165, v112, v113
	v_add_f32_e32 v112, v112, v113
	v_add_f32_e32 v216, v216, v110
	v_add_f32_e32 v216, v216, v112
	v_mov_b32_e32 v240, 0x61
	v_mov_b32_e32 v241, 0x42800000
	v_mov_b32_e32 v242, 0xf149f2ca
	v_not_b32_e32 v243, 63
	s_waitcnt vmcnt(0)
	s_cmp_eq_u32 s101, 0
	s_cbranch_scc0 .Lpp_nb_p2
	s_barrier
